# CMP2 importance accumulation: dropped the barrier between the two read-modify-write steps of the same wave (4 of 8 barriers per key block)
# baseline (speedup 1.0000x reference)
; template <int MODE> ...
;     ...
;       if (MODE == M_CMP2) {
;         const int jb = (kbase >> 2) + h;
;         for (int rr = 0; rr < 4; ++rr) {
;           if (w == rr) {
; #pragma unroll
;             for (int nb = 0; nb < 2; ++nb)
; #pragma unroll
;               for (int a4 = 0; a4 < 4; ++a4) imp[(nb * 32 + r) * 65 + jb + 2 * a4] += mainv[nb][a4];
;           }
;           __syncthreads();
;           if (w == rr) {
; #pragma unroll
;             for (int nb = 0; nb < 2; ++nb)
; #pragma unroll
;               for (int a4 = 0; a4 < 4; ++a4) imp[(nb * 32 + r) * 65 + jb + 2 * a4 + 1] += spill[nb][a4];
;           }
;           __syncthreads();
;         }
.LBB0_697:
	s_or_b64 exec, exec, s[0:1]
	v_mul_f32_e32 v14, 0.5, v56
	v_mul_f32_e32 v15, 0.5, v57
	v_mul_f32_e32 v12, 0.5, v58
	v_mul_f32_e32 v13, 0.5, v59
	v_mul_f32_e32 v10, 0.5, v5
	v_mul_f32_e32 v11, 0.5, v6
	v_mul_f32_e32 v5, 0.5, v9
	v_mul_f32_e32 v6, 0.5, v26
	s_waitcnt lgkmcnt(0)
	s_and_saveexec_b64 s[0:1], s[42:43]
	s_cbranch_execz .LBB0_699
	ds_read2_b32 v[26:27], v8 offset0:129 offset1:131
	ds_read2_b32 v[28:29], v8 offset0:133 offset1:135
	s_waitcnt lgkmcnt(1)
	v_add_f32_e32 v9, v14, v26
	v_add_f32_e32 v26, v15, v27
	s_waitcnt lgkmcnt(0)
	v_add_f32_e32 v27, v12, v28
	v_add_f32_e32 v28, v13, v29
	ds_write2_b32 v8, v9, v26 offset0:129 offset1:131
	ds_write2_b32 v8, v27, v28 offset0:133 offset1:135
	ds_read2_b32 v[26:27], v17 offset0:129 offset1:131
	ds_read2_b32 v[28:29], v17 offset0:133 offset1:135
	s_waitcnt lgkmcnt(1)
	v_add_f32_e32 v9, v10, v26
	v_add_f32_e32 v26, v11, v27
	s_waitcnt lgkmcnt(0)
	v_add_f32_e32 v27, v5, v28
	ds_write2_b32 v17, v9, v26 offset0:129 offset1:131
	v_add_f32_e32 v9, v6, v29
	ds_write2_b32 v17, v27, v9 offset0:133 offset1:135

; template <int MODE> ...
;     ...
;       if (MODE == M_CMP2) {
;         const int jb = (kbase >> 2) + h;
;         for (int rr = 0; rr < 4; ++rr) {
;           if (w == rr) {
; #pragma unroll
;             for (int nb = 0; nb < 2; ++nb)
; #pragma unroll
;               for (int a4 = 0; a4 < 4; ++a4) imp[(nb * 32 + r) * 65 + jb + 2 * a4] += mainv[nb][a4];
;           }
;           __syncthreads();
;           if (w == rr) {
; #pragma unroll
;             for (int nb = 0; nb < 2; ++nb)
; #pragma unroll
;               for (int a4 = 0; a4 < 4; ++a4) imp[(nb * 32 + r) * 65 + jb + 2 * a4 + 1] += spill[nb][a4];
;           }
;           __syncthreads();
;         }
.LBB0_701:
	s_or_b64 exec, exec, s[0:1]
	s_waitcnt lgkmcnt(0)
	s_and_saveexec_b64 s[0:1], s[44:45]
	s_cbranch_execz .LBB0_703
	ds_read2_b32 v[16:17], v8 offset0:129 offset1:131
	ds_read2_b32 v[26:27], v8 offset0:133 offset1:135
	s_waitcnt lgkmcnt(1)
	v_add_f32_e32 v16, v14, v16
	v_add_f32_e32 v17, v15, v17
	ds_write2_b32 v8, v16, v17 offset0:129 offset1:131
	s_waitcnt lgkmcnt(1)
	v_add_f32_e32 v16, v12, v26
	v_add_f32_e32 v17, v13, v27
	ds_write2_b32 v8, v16, v17 offset0:133 offset1:135
	ds_read2_b32 v[16:17], v9 offset0:161 offset1:163
	s_waitcnt lgkmcnt(0)
	v_add_f32_e32 v16, v10, v16
	v_add_f32_e32 v17, v11, v17
	ds_write2_b32 v9, v16, v17 offset0:161 offset1:163
	ds_read2_b32 v[16:17], v9 offset0:165 offset1:167
	s_waitcnt lgkmcnt(0)
	v_add_f32_e32 v16, v5, v16
	v_add_f32_e32 v17, v6, v17
	ds_write2_b32 v9, v16, v17 offset0:165 offset1:167

; template <int MODE> ...
;     ...
;       if (MODE == M_CMP2) {
;         const int jb = (kbase >> 2) + h;
;         for (int rr = 0; rr < 4; ++rr) {
;           if (w == rr) {
; #pragma unroll
;             for (int nb = 0; nb < 2; ++nb)
; #pragma unroll
;               for (int a4 = 0; a4 < 4; ++a4) imp[(nb * 32 + r) * 65 + jb + 2 * a4] += mainv[nb][a4];
;           }
;           __syncthreads();
;           if (w == rr) {
; #pragma unroll
;             for (int nb = 0; nb < 2; ++nb)
; #pragma unroll
;               for (int a4 = 0; a4 < 4; ++a4) imp[(nb * 32 + r) * 65 + jb + 2 * a4 + 1] += spill[nb][a4];
;           }
;           __syncthreads();
;         }
.LBB0_705:
	s_or_b64 exec, exec, s[0:1]
	s_waitcnt lgkmcnt(0)
	s_and_saveexec_b64 s[0:1], s[46:47]
	s_cbranch_execz .LBB0_707
	ds_read2_b32 v[16:17], v8 offset0:129 offset1:131
	ds_read2_b32 v[26:27], v8 offset0:133 offset1:135
	s_waitcnt lgkmcnt(1)
	v_add_f32_e32 v16, v14, v16
	v_add_f32_e32 v17, v15, v17
	ds_write2_b32 v8, v16, v17 offset0:129 offset1:131
	s_waitcnt lgkmcnt(1)
	v_add_f32_e32 v16, v12, v26
	v_add_f32_e32 v17, v13, v27
	ds_write2_b32 v8, v16, v17 offset0:133 offset1:135
	ds_read2_b32 v[16:17], v9 offset0:161 offset1:163
	s_waitcnt lgkmcnt(0)
	v_add_f32_e32 v16, v10, v16
	v_add_f32_e32 v17, v11, v17
	ds_write2_b32 v9, v16, v17 offset0:161 offset1:163
	ds_read2_b32 v[16:17], v9 offset0:165 offset1:167
	s_waitcnt lgkmcnt(0)
	v_add_f32_e32 v16, v5, v16
	v_add_f32_e32 v17, v6, v17
	ds_write2_b32 v9, v16, v17 offset0:165 offset1:167

; template <int MODE> ...
;     ...
;       if (MODE == M_CMP2) {
;         const int jb = (kbase >> 2) + h;
;         for (int rr = 0; rr < 4; ++rr) {
;           if (w == rr) {
; #pragma unroll
;             for (int nb = 0; nb < 2; ++nb)
; #pragma unroll
;               for (int a4 = 0; a4 < 4; ++a4) imp[(nb * 32 + r) * 65 + jb + 2 * a4] += mainv[nb][a4];
;           }
;           __syncthreads();
;           if (w == rr) {
; #pragma unroll
;             for (int nb = 0; nb < 2; ++nb)
; #pragma unroll
;               for (int a4 = 0; a4 < 4; ++a4) imp[(nb * 32 + r) * 65 + jb + 2 * a4 + 1] += spill[nb][a4];
;           }
;           __syncthreads();
;         }
.LBB0_709:
	s_or_b64 exec, exec, s[0:1]
	s_waitcnt lgkmcnt(0)
	s_and_saveexec_b64 s[0:1], s[48:49]
	s_cbranch_execz .LBB0_694
	ds_read2_b32 v[2:3], v8 offset0:129 offset1:131
	ds_read2_b32 v[16:17], v8 offset0:133 offset1:135
	s_waitcnt lgkmcnt(1)
	v_add_f32_e32 v2, v14, v2
	v_add_f32_e32 v3, v15, v3
	ds_write2_b32 v8, v2, v3 offset0:129 offset1:131
	s_waitcnt lgkmcnt(1)
	v_add_f32_e32 v2, v12, v16
	v_add_f32_e32 v3, v13, v17
	ds_write2_b32 v8, v2, v3 offset0:133 offset1:135
	ds_read2_b32 v[2:3], v9 offset0:161 offset1:163
	s_waitcnt lgkmcnt(0)
	v_add_f32_e32 v2, v10, v2
	v_add_f32_e32 v3, v11, v3
	ds_write2_b32 v9, v2, v3 offset0:161 offset1:163
	ds_read2_b32 v[2:3], v9 offset0:165 offset1:167
	s_waitcnt lgkmcnt(0)
	v_add_f32_e32 v2, v5, v2
	v_add_f32_e32 v3, v6, v3
	ds_write2_b32 v9, v2, v3 offset0:165 offset1:167
	s_branch .LBB0_694
